# P3 rwkv_prep row loop: two alternating load-target register sets so the window rotation copies a row loaded two iterations earlier; loop-head wait vmcnt(0) -> vmcnt(7)
# speedup vs baseline: 1.0020x; 1.0014x over previous
; #define GAS __attribute__((address_space(1)))
; __device__ __forceinline__ void prep_load_row(const bf16* Z, int row, int c, v4u (&z)[3]) {
; #pragma unroll
;     for (int qn = 0; qn < 3; ++qn) z[qn] = *(const GAS v4u*)(Z + (size_t)row * ZLD + (qn == 0 ? ZR : (qn == 1 ? ZKB : ZVB)) + c);
; __device__ __forceinline__ void rwkv_prep_wave(const Args& a, int gw, int NGW, int lane) {
;     ...
;     const int nq = NGW >> 2, wq = gw >> 2, per = (MALL + nq - 1) / nq;
;     const int r0 = wq * per, r1 = (r0 + per < MALL) ? r0 + per : MALL;
;     if (r0 >= r1) return;
;     const v4u z4 = {0u, 0u, 0u, 0u};
;     v4u P[3] = {z4, z4, z4}, C[3], N[3] = {z4, z4, z4}, N2[3] = {z4, z4, z4}, N3[3];
;     if (r0 > 0) prep_load_row(Z, r0 - 1, c, P);
;     prep_load_row(Z, r0, c, C);
;     if (r0 + 1 < MALL) prep_load_row(Z, r0 + 1, c, N);
;     if (r0 + 2 < MALL && r0 + 2 <= r1) prep_load_row(Z, r0 + 2, c, N2);
;     for (int row = r0; row < r1; ++row) {
; #pragma unroll
;         for (int qn = 0; qn < 3; ++qn) N3[qn] = z4;
;         if (row + 3 < MALL && row + 3 <= r1) prep_load_row(Z, row + 3, c, N3);
.LBB0_477:
	s_lshl_b64 s[0:1], s[4:5], 12
	v_mov_b32_e32 v82, 0
	s_add_u32 s0, s24, s0
	v_mov_b32_e32 v85, v82
	s_addc_u32 s1, s25, s1
	v_lshl_add_u64 v[134:135], s[50:51], 0, v[84:85]
	v_lshl_add_u64 v[84:85], s[0:1], 0, v[84:85]
	s_mov_b64 s[0:1], 0x5e800000
	s_waitcnt vmcnt(19)
	v_mov_b32_e32 v136, v124
	v_mov_b32_e32 v137, v8
	v_mov_b32_e32 v8, v125
	v_mov_b32_e32 v124, v122
	v_mov_b32_e32 v125, v6
	v_mov_b32_e32 v6, v123
	v_mov_b32_e32 v122, v104
	v_mov_b32_e32 v123, v4
	v_mov_b32_e32 v4, v105
	v_mov_b32_e32 v138, v102
	v_mov_b32_e32 v139, v2
	v_mov_b32_e32 v2, v103
	s_waitcnt vmcnt(13)
	v_mov_b32_e32 v140, v128
	v_mov_b32_e32 v141, v24
	v_mov_b32_e32 v24, v129
	v_mov_b32_e32 v128, v126
	v_mov_b32_e32 v129, v22
	v_mov_b32_e32 v22, v127
	v_mov_b32_e32 v126, v108
	v_mov_b32_e32 v127, v20
	v_mov_b32_e32 v20, v109
	v_mov_b32_e32 v142, v106
	v_mov_b32_e32 v143, v18
	v_mov_b32_e32 v18, v107
	s_waitcnt vmcnt(7)
	v_mov_b32_e32 v144, v132
	v_mov_b32_e32 v145, v40
	v_mov_b32_e32 v40, v133
	v_mov_b32_e32 v132, v130
	v_mov_b32_e32 v133, v38
	v_mov_b32_e32 v38, v131
	v_mov_b32_e32 v130, v112
	v_mov_b32_e32 v131, v36
	v_mov_b32_e32 v36, v113
	v_mov_b32_e32 v146, v110
	v_mov_b32_e32 v147, v34
	v_mov_b32_e32 v34, v111
	v_lshl_add_u64 v[148:149], v[84:85], 0, s[0:1]
	s_mov_b32 s5, 0xf800000
	v_mov_b32_e32 v1, 0x260
	s_mov_b32 s11, 0x4200000
	s_mov_b32 s12, 0x8400000
	s_mov_b64 s[6:7], 0x1000
	v_mov_b32_e32 v150, 0x6c00
	s_waitcnt vmcnt(0)
	s_mov_b32 s98, 0
	s_branch .LBB0_480

; #define GAS __attribute__((address_space(1)))
; __device__ __forceinline__ void prep_load_row(const bf16* Z, int row, int c, v4u (&z)[3]) {
; #pragma unroll
;     for (int qn = 0; qn < 3; ++qn) z[qn] = *(const GAS v4u*)(Z + (size_t)row * ZLD + (qn == 0 ? ZR : (qn == 1 ? ZKB : ZVB)) + c);
; __device__ __forceinline__ void rwkv_prep_wave(const Args& a, int gw, int NGW, int lane) {
;     ...
;     for (int row = r0; row < r1; ++row) {
; #pragma unroll
;         for (int qn = 0; qn < 3; ++qn) N3[qn] = z4;
;         if (row + 3 < MALL && row + 3 <= r1) prep_load_row(Z, row + 3, c, N3);
;     ...
;         for (int qn = 0; qn < 3; ++qn) { P[qn] = C[qn]; C[qn] = N[qn]; N[qn] = N2[qn]; N2[qn] = N3[qn]; }
.LBB0_480:
	s_add_i32 s0, s4, 3
	s_cmpk_gt_i32 s4, 0x41fc
	s_waitcnt vmcnt(7)
	v_mov_b64_e32 v[104:105], v[68:69]
	v_mov_b64_e32 v[108:109], v[64:65]
	v_mov_b64_e32 v[112:113], v[60:61]
	s_cselect_b64 s[14:15], -1, 0
	s_cmp_gt_i32 s0, s10
	v_mov_b64_e32 v[102:103], v[66:67]
	v_mov_b64_e32 v[106:107], v[62:63]
	v_mov_b64_e32 v[110:111], v[58:59]
	s_cselect_b64 s[16:17], -1, 0
	s_or_b64 s[14:15], s[14:15], s[16:17]
	s_and_b64 vcc, exec, s[14:15]
	s_xor_b32 s98, s98, 1
	s_cbranch_scc1 .Lp3_setb
	v_mov_b64_e32 v[66:67], v[94:95]
	v_mov_b64_e32 v[62:63], v[90:91]
	v_mov_b64_e32 v[58:59], v[86:87]
	v_mov_b64_e32 v[68:69], v[96:97]
	v_mov_b64_e32 v[64:65], v[92:93]
	v_mov_b64_e32 v[60:61], v[88:89]
	s_cbranch_vccz .LBB0_478
	v_mov_b32_e32 v84, v82
	v_mov_b32_e32 v85, v82
	v_mov_b32_e32 v83, v82
	v_mov_b64_e32 v[88:89], v[84:85]
	v_mov_b64_e32 v[92:93], v[84:85]
	v_mov_b64_e32 v[96:97], v[84:85]
	v_mov_b64_e32 v[86:87], v[82:83]
	v_mov_b64_e32 v[90:91], v[82:83]
	v_mov_b64_e32 v[94:95], v[82:83]
	s_branch .LBB0_479
.Lp3_setb:
	v_mov_b64_e32 v[66:67], v[78:79]
	v_mov_b64_e32 v[62:63], v[74:75]
	v_mov_b64_e32 v[58:59], v[70:71]
	v_mov_b64_e32 v[68:69], v[80:81]
	v_mov_b64_e32 v[64:65], v[76:77]
	v_mov_b64_e32 v[60:61], v[72:73]
	s_cbranch_vccz .Lp3_ldb
	v_mov_b32_e32 v84, v82
	v_mov_b32_e32 v85, v82
	v_mov_b32_e32 v83, v82
	v_mov_b64_e32 v[72:73], v[84:85]
	v_mov_b64_e32 v[76:77], v[84:85]
	v_mov_b64_e32 v[80:81], v[84:85]
	v_mov_b64_e32 v[70:71], v[82:83]
	v_mov_b64_e32 v[74:75], v[82:83]
	v_mov_b64_e32 v[78:79], v[82:83]
	s_branch .LBB0_479
.Lp3_ldb:
	v_mad_i64_i32 v[84:85], s[0:1], s0, v150, v[134:135]
	v_add_co_u32_e32 v70, vcc, 0x2000, v84
	s_nop 1
	v_addc_co_u32_e32 v71, vcc, 0, v85, vcc
	v_add_co_u32_e32 v74, vcc, 0x3000, v84
	s_nop 1
	v_addc_co_u32_e32 v75, vcc, 0, v85, vcc
	v_add_co_u32_e32 v84, vcc, 0x4000, v84
	global_load_dwordx4 v[70:73], v[70:71], off offset:2048
	s_nop 0
	global_load_dwordx4 v[74:77], v[74:75], off offset:2048
	v_addc_co_u32_e32 v85, vcc, 0, v85, vcc
	global_load_dwordx4 v[78:81], v[84:85], off offset:2048
	s_branch .LBB0_479
